# S5 scan: MFMA output to scan layout via v_permlane32_swap in registers (no LDS transpose), scalar fmac recurrence; plus conv_part moved to idle GLU-phase workgroups
# speedup vs baseline: 1.0176x; 1.0176x over previous
.LBB0_947:
	v_mfma_f32_32x32x16_bf16 v[0:15], v[84:87], v[48:51], 0
	v_mfma_f32_32x32x16_bf16 v[32:47], v[84:87], v[56:59], 0
	v_mfma_f32_32x32x16_bf16 v[16:31], v[84:87], v[52:55], 0
	v_mfma_f32_32x32x16_bf16 v[144:159], v[84:87], v[60:63], 0
	s_nop 9
	v_permlane32_swap_b32_e32 v0, v32
	v_permlane32_swap_b32_e32 v1, v33
	v_permlane32_swap_b32_e32 v2, v34
	v_permlane32_swap_b32_e32 v3, v35
	v_permlane32_swap_b32_e32 v4, v36
	v_permlane32_swap_b32_e32 v5, v37
	v_permlane32_swap_b32_e32 v6, v38
	v_permlane32_swap_b32_e32 v7, v39
	v_permlane32_swap_b32_e32 v8, v40
	v_permlane32_swap_b32_e32 v9, v41
	v_permlane32_swap_b32_e32 v10, v42
	v_permlane32_swap_b32_e32 v11, v43
	v_permlane32_swap_b32_e32 v12, v44
	v_permlane32_swap_b32_e32 v13, v45
	v_permlane32_swap_b32_e32 v14, v46
	v_permlane32_swap_b32_e32 v15, v47
	v_permlane32_swap_b32_e32 v16, v144
	v_permlane32_swap_b32_e32 v17, v145
	v_permlane32_swap_b32_e32 v18, v146
	v_permlane32_swap_b32_e32 v19, v147
	v_permlane32_swap_b32_e32 v20, v148
	v_permlane32_swap_b32_e32 v21, v149
	v_permlane32_swap_b32_e32 v22, v150
	v_permlane32_swap_b32_e32 v23, v151
	v_permlane32_swap_b32_e32 v24, v152
	v_permlane32_swap_b32_e32 v25, v153
	v_permlane32_swap_b32_e32 v26, v154
	v_permlane32_swap_b32_e32 v27, v155
	v_permlane32_swap_b32_e32 v28, v156
	v_permlane32_swap_b32_e32 v29, v157
	v_permlane32_swap_b32_e32 v30, v158
	v_permlane32_swap_b32_e32 v31, v159
	v_fmac_f32_e32 v0, v106, v111
	v_fmac_f32_e32 v16, v107, v110
	v_fmac_f32_e32 v0, v108, v110
	v_fmac_f32_e32 v16, v109, v111
	v_cvt_pk_bf16_f32 v160, v0, v16
	ds_write_b32 v99, v160
	v_fmac_f32_e32 v1, v106, v16
	v_fmac_f32_e32 v17, v107, v0
	v_fmac_f32_e32 v1, v108, v0
	v_fmac_f32_e32 v17, v109, v16
	v_cvt_pk_bf16_f32 v161, v1, v17
	ds_write_b32 v99, v161 offset:528
	v_fmac_f32_e32 v2, v106, v17
	v_fmac_f32_e32 v18, v107, v1
	v_fmac_f32_e32 v2, v108, v1
	v_fmac_f32_e32 v18, v109, v17
	v_cvt_pk_bf16_f32 v162, v2, v18
	ds_write_b32 v99, v162 offset:1056
	v_fmac_f32_e32 v3, v106, v18
	v_fmac_f32_e32 v19, v107, v2
	v_fmac_f32_e32 v3, v108, v2
	v_fmac_f32_e32 v19, v109, v18
	v_cvt_pk_bf16_f32 v163, v3, v19
	ds_write_b32 v99, v163 offset:1584
	v_fmac_f32_e32 v32, v106, v19
	v_fmac_f32_e32 v144, v107, v3
	v_fmac_f32_e32 v32, v108, v3
	v_fmac_f32_e32 v144, v109, v19
	v_cvt_pk_bf16_f32 v160, v32, v144
	ds_write_b32 v99, v160 offset:2112
	v_fmac_f32_e32 v33, v106, v144
	v_fmac_f32_e32 v145, v107, v32
	v_fmac_f32_e32 v33, v108, v32
	v_fmac_f32_e32 v145, v109, v144
	v_cvt_pk_bf16_f32 v161, v33, v145
	ds_write_b32 v99, v161 offset:2640
	v_fmac_f32_e32 v34, v106, v145
	v_fmac_f32_e32 v146, v107, v33
	v_fmac_f32_e32 v34, v108, v33
	v_fmac_f32_e32 v146, v109, v145
	v_cvt_pk_bf16_f32 v162, v34, v146
	ds_write_b32 v99, v162 offset:3168
	v_fmac_f32_e32 v35, v106, v146
	v_fmac_f32_e32 v147, v107, v34
	v_fmac_f32_e32 v35, v108, v34
	v_fmac_f32_e32 v147, v109, v146
	v_cvt_pk_bf16_f32 v163, v35, v147
	ds_write_b32 v99, v163 offset:3696
	v_fmac_f32_e32 v4, v106, v147
	v_fmac_f32_e32 v20, v107, v35
	v_fmac_f32_e32 v4, v108, v35
	v_fmac_f32_e32 v20, v109, v147
	v_cvt_pk_bf16_f32 v160, v4, v20
	ds_write_b32 v99, v160 offset:4224
	v_fmac_f32_e32 v5, v106, v20
	v_fmac_f32_e32 v21, v107, v4
	v_fmac_f32_e32 v5, v108, v4
	v_fmac_f32_e32 v21, v109, v20
	v_cvt_pk_bf16_f32 v161, v5, v21
	ds_write_b32 v99, v161 offset:4752
	v_fmac_f32_e32 v6, v106, v21
	v_fmac_f32_e32 v22, v107, v5
	v_fmac_f32_e32 v6, v108, v5
	v_fmac_f32_e32 v22, v109, v21
	v_cvt_pk_bf16_f32 v162, v6, v22
	ds_write_b32 v99, v162 offset:5280
	v_fmac_f32_e32 v7, v106, v22
	v_fmac_f32_e32 v23, v107, v6
	v_fmac_f32_e32 v7, v108, v6
	v_fmac_f32_e32 v23, v109, v22
	v_cvt_pk_bf16_f32 v163, v7, v23
	ds_write_b32 v99, v163 offset:5808
	v_fmac_f32_e32 v36, v106, v23
	v_fmac_f32_e32 v148, v107, v7
	v_fmac_f32_e32 v36, v108, v7
	v_fmac_f32_e32 v148, v109, v23
	v_cvt_pk_bf16_f32 v160, v36, v148
	ds_write_b32 v99, v160 offset:6336
	v_fmac_f32_e32 v37, v106, v148
	v_fmac_f32_e32 v149, v107, v36
	v_fmac_f32_e32 v37, v108, v36
	v_fmac_f32_e32 v149, v109, v148
	v_cvt_pk_bf16_f32 v161, v37, v149
	ds_write_b32 v99, v161 offset:6864
	v_fmac_f32_e32 v38, v106, v149
	v_fmac_f32_e32 v150, v107, v37
	v_fmac_f32_e32 v38, v108, v37
	v_fmac_f32_e32 v150, v109, v149
	v_cvt_pk_bf16_f32 v162, v38, v150
	ds_write_b32 v99, v162 offset:7392
	v_fmac_f32_e32 v39, v106, v150
	v_fmac_f32_e32 v151, v107, v38
	v_fmac_f32_e32 v39, v108, v38
	v_fmac_f32_e32 v151, v109, v150
	v_cvt_pk_bf16_f32 v163, v39, v151
	ds_write_b32 v99, v163 offset:7920
	v_fmac_f32_e32 v8, v106, v151
	v_fmac_f32_e32 v24, v107, v39
	v_fmac_f32_e32 v8, v108, v39
	v_fmac_f32_e32 v24, v109, v151
	v_cvt_pk_bf16_f32 v160, v8, v24
	ds_write_b32 v99, v160 offset:8448
	v_fmac_f32_e32 v9, v106, v24
	v_fmac_f32_e32 v25, v107, v8
	v_fmac_f32_e32 v9, v108, v8
	v_fmac_f32_e32 v25, v109, v24
	v_cvt_pk_bf16_f32 v161, v9, v25
	ds_write_b32 v99, v161 offset:8976
	v_fmac_f32_e32 v10, v106, v25
	v_fmac_f32_e32 v26, v107, v9
	v_fmac_f32_e32 v10, v108, v9
	v_fmac_f32_e32 v26, v109, v25
	v_cvt_pk_bf16_f32 v162, v10, v26
	ds_write_b32 v99, v162 offset:9504
	v_fmac_f32_e32 v11, v106, v26
	v_fmac_f32_e32 v27, v107, v10
	v_fmac_f32_e32 v11, v108, v10
	v_fmac_f32_e32 v27, v109, v26
	v_cvt_pk_bf16_f32 v163, v11, v27
	ds_write_b32 v99, v163 offset:10032
	v_fmac_f32_e32 v40, v106, v27
	v_fmac_f32_e32 v152, v107, v11
	v_fmac_f32_e32 v40, v108, v11
	v_fmac_f32_e32 v152, v109, v27
	v_cvt_pk_bf16_f32 v160, v40, v152
	ds_write_b32 v99, v160 offset:10560
	v_fmac_f32_e32 v41, v106, v152
	v_fmac_f32_e32 v153, v107, v40
	v_fmac_f32_e32 v41, v108, v40
	v_fmac_f32_e32 v153, v109, v152
	v_cvt_pk_bf16_f32 v161, v41, v153
	ds_write_b32 v99, v161 offset:11088
	v_fmac_f32_e32 v42, v106, v153
	v_fmac_f32_e32 v154, v107, v41
	v_fmac_f32_e32 v42, v108, v41
	v_fmac_f32_e32 v154, v109, v153
	v_cvt_pk_bf16_f32 v162, v42, v154
	ds_write_b32 v99, v162 offset:11616
	v_fmac_f32_e32 v43, v106, v154
	v_fmac_f32_e32 v155, v107, v42
	v_fmac_f32_e32 v43, v108, v42
	v_fmac_f32_e32 v155, v109, v154
	v_cvt_pk_bf16_f32 v163, v43, v155
	ds_write_b32 v99, v163 offset:12144
	v_fmac_f32_e32 v12, v106, v155
	v_fmac_f32_e32 v28, v107, v43
	v_fmac_f32_e32 v12, v108, v43
	v_fmac_f32_e32 v28, v109, v155
	v_cvt_pk_bf16_f32 v160, v12, v28
	ds_write_b32 v99, v160 offset:12672
	v_fmac_f32_e32 v13, v106, v28
	v_fmac_f32_e32 v29, v107, v12
	v_fmac_f32_e32 v13, v108, v12
	v_fmac_f32_e32 v29, v109, v28
	v_cvt_pk_bf16_f32 v161, v13, v29
	ds_write_b32 v99, v161 offset:13200
	v_fmac_f32_e32 v14, v106, v29
	v_fmac_f32_e32 v30, v107, v13
	v_fmac_f32_e32 v14, v108, v13
	v_fmac_f32_e32 v30, v109, v29
	v_cvt_pk_bf16_f32 v162, v14, v30
	ds_write_b32 v99, v162 offset:13728
	v_fmac_f32_e32 v15, v106, v30
	v_fmac_f32_e32 v31, v107, v14
	v_fmac_f32_e32 v15, v108, v14
	v_fmac_f32_e32 v31, v109, v30
	v_cvt_pk_bf16_f32 v163, v15, v31
	ds_write_b32 v99, v163 offset:14256
	v_fmac_f32_e32 v44, v106, v31
	v_fmac_f32_e32 v156, v107, v15
	v_fmac_f32_e32 v44, v108, v15
	v_fmac_f32_e32 v156, v109, v31
	v_cvt_pk_bf16_f32 v160, v44, v156
	ds_write_b32 v99, v160 offset:14784
	v_fmac_f32_e32 v45, v106, v156
	v_fmac_f32_e32 v157, v107, v44
	v_fmac_f32_e32 v45, v108, v44
	v_fmac_f32_e32 v157, v109, v156
	v_cvt_pk_bf16_f32 v161, v45, v157
	ds_write_b32 v99, v161 offset:15312
	v_fmac_f32_e32 v46, v106, v157
	v_fmac_f32_e32 v158, v107, v45
	v_fmac_f32_e32 v46, v108, v45
	v_fmac_f32_e32 v158, v109, v157
	v_cvt_pk_bf16_f32 v162, v46, v158
	ds_write_b32 v99, v162 offset:15840
	v_fmac_f32_e32 v47, v106, v158
	v_fmac_f32_e32 v159, v107, v46
	v_fmac_f32_e32 v47, v108, v46
	v_fmac_f32_e32 v159, v109, v158
	v_cvt_pk_bf16_f32 v163, v47, v159
	ds_write_b32 v99, v163 offset:16368
	v_mov_b32_e32 v110, v47
	v_mov_b32_e32 v111, v159
	s_waitcnt lgkmcnt(0)
	ds_read_b128 v[0:3], v119
	ds_read_b128 v[4:7], v119 offset:64
	v_lshl_add_u32 v8, s14, 5, v96
	s_add_i32 s14, s14, 1
	s_waitcnt vmcnt(0)
	v_mov_b64_e32 v[86:87], v[82:83]
	s_cmp_lg_u32 s14, 8
	v_mov_b64_e32 v[84:85], v[80:81]
	s_waitcnt lgkmcnt(1)
	v_mfma_f32_16x16x32_bf16 v[0:3], v[0:3], v[64:67], 0
	s_waitcnt lgkmcnt(0)
	v_mfma_f32_16x16x32_bf16 v[0:3], v[4:7], v[68:71], v[0:3]
	ds_read_b128 v[4:7], v119 offset:128
	s_waitcnt lgkmcnt(0)
	v_mfma_f32_16x16x32_bf16 v[0:3], v[4:7], v[72:75], v[0:3]
	ds_read_b128 v[4:7], v119 offset:192
	s_waitcnt lgkmcnt(0)
	v_mfma_f32_16x16x32_bf16 v[0:3], v[4:7], v[76:79], v[0:3]
	v_sub_u32_e32 v4, 0xff, v8
	v_cndmask_b32_e64 v4, v4, v8, s[8:9]
	v_add_u32_e32 v4, s10, v4
	v_ashrrev_i32_e32 v5, 31, v4
	v_lshlrev_b64 v[4:5], 11, v[4:5]
	v_lshl_add_u64 v[4:5], v[114:115], 0, v[4:5]
	s_nop 1
	global_store_dword v[4:5], v0, off
	v_or_b32_e32 v0, 1, v8
	v_sub_u32_e32 v4, 0xff, v0
	v_cndmask_b32_e64 v0, v4, v0, s[8:9]
	v_add_u32_e32 v4, s10, v0
	v_ashrrev_i32_e32 v5, 31, v4
	v_lshlrev_b64 v[4:5], 11, v[4:5]
	v_lshl_add_u64 v[4:5], v[114:115], 0, v[4:5]
	v_or_b32_e32 v0, 2, v8
	global_store_dword v[4:5], v1, off
	v_sub_u32_e32 v1, 0xff, v0
	v_cndmask_b32_e64 v0, v1, v0, s[8:9]
	v_add_u32_e32 v0, s10, v0
	v_ashrrev_i32_e32 v1, 31, v0
	v_lshlrev_b64 v[0:1], 11, v[0:1]
	v_lshl_add_u64 v[0:1], v[114:115], 0, v[0:1]
	global_store_dword v[0:1], v2, off
	v_or_b32_e32 v0, 3, v8
	v_sub_u32_e32 v1, 0xff, v0
	v_cndmask_b32_e64 v0, v1, v0, s[8:9]
	v_add_u32_e32 v0, s10, v0
	v_ashrrev_i32_e32 v1, 31, v0
	v_lshlrev_b64 v[0:1], 11, v[0:1]
	v_lshl_add_u64 v[0:1], v[114:115], 0, v[0:1]
	global_store_dword v[0:1], v3, off
	ds_read_b128 v[0:3], v119 offset:8448
	ds_read_b128 v[4:7], v119 offset:8512
	s_waitcnt lgkmcnt(1)
	v_mfma_f32_16x16x32_bf16 v[0:3], v[0:3], v[64:67], 0
	s_waitcnt lgkmcnt(0)
	v_mfma_f32_16x16x32_bf16 v[0:3], v[4:7], v[68:71], v[0:3]
	ds_read_b128 v[4:7], v119 offset:8576
	s_waitcnt lgkmcnt(0)
	v_mfma_f32_16x16x32_bf16 v[0:3], v[4:7], v[72:75], v[0:3]
	ds_read_b128 v[4:7], v119 offset:8640
	s_waitcnt lgkmcnt(0)
	v_mfma_f32_16x16x32_bf16 v[0:3], v[4:7], v[76:79], v[0:3]
	v_add_u32_e32 v4, 16, v8
	v_sub_u32_e32 v5, 0xef, v8
	v_cndmask_b32_e64 v4, v5, v4, s[8:9]
	v_add_u32_e32 v4, s10, v4
	v_ashrrev_i32_e32 v5, 31, v4
	v_lshlrev_b64 v[4:5], 11, v[4:5]
	v_lshl_add_u64 v[4:5], v[114:115], 0, v[4:5]
	s_nop 0
	global_store_dword v[4:5], v0, off
	v_add_u32_e32 v0, 17, v8
	v_sub_u32_e32 v4, 0xee, v8
	v_cndmask_b32_e64 v0, v4, v0, s[8:9]
	v_add_u32_e32 v4, s10, v0
	v_ashrrev_i32_e32 v5, 31, v4
	v_lshlrev_b64 v[4:5], 11, v[4:5]
	v_lshl_add_u64 v[4:5], v[114:115], 0, v[4:5]
	global_store_dword v[4:5], v1, off
	v_add_u32_e32 v0, 18, v8
	v_sub_u32_e32 v1, 0xed, v8
	v_cndmask_b32_e64 v0, v1, v0, s[8:9]
	v_add_u32_e32 v0, s10, v0
	v_ashrrev_i32_e32 v1, 31, v0
	v_lshlrev_b64 v[0:1], 11, v[0:1]
	v_lshl_add_u64 v[0:1], v[114:115], 0, v[0:1]
	global_store_dword v[0:1], v2, off
	v_add_u32_e32 v0, 19, v8
	v_sub_u32_e32 v1, 0xec, v8
	v_cndmask_b32_e64 v0, v1, v0, s[8:9]
	v_add_u32_e32 v0, s10, v0
	v_ashrrev_i32_e32 v1, 31, v0
	v_lshlrev_b64 v[0:1], 11, v[0:1]
	v_lshl_add_u64 v[0:1], v[114:115], 0, v[0:1]
	global_store_dword v[0:1], v3, off
	s_waitcnt lgkmcnt(0)
	s_cbranch_scc1 .LBB0_945
	s_ashr_i32 s13, s12, 31
	s_lshl_b64 s[14:15], s[12:13], 13
	s_or_b64 s[14:15], s[14:15], s[84:85]
	s_add_u32 s14, s14, s96
	s_addc_u32 s15, s15, 0
	v_lshl_add_u64 v[0:1], s[14:15], 0, v[88:89]
	s_load_dwordx2 s[14:15], s[4:5], 0x100
	s_waitcnt lgkmcnt(0)
	v_lshlrev_b64 v[0:1], 2, v[0:1]
	v_lshl_add_u64 v[2:3], s[14:15], 0, v[0:1]
	s_brev_b32 s14, 32
	v_add_co_u32_e32 v2, vcc, s14, v2
	s_addk_i32 s10, 0x2000
	s_nop 0
	v_addc_co_u32_e32 v3, vcc, 0, v3, vcc
	global_store_dword v[2:3], v110, off
	s_load_dwordx2 s[14:15], s[4:5], 0x100
	s_waitcnt lgkmcnt(0)
	s_lshl_b32 s96, s11, 1
	v_lshl_add_u64 v[0:1], s[14:15], 0, v[0:1]
	s_mov_b32 s14, 0x4100000
	v_add_co_u32_e32 v0, vcc, s14, v0
	v_mov_b32_e32 v72, 0
	s_nop 0
	v_addc_co_u32_e32 v1, vcc, 0, v1, vcc
	global_store_dword v[0:1], v111, off
	v_or_b32_e32 v0, s10, v117
	v_ashrrev_i32_e32 v1, 31, v0
	v_lshlrev_b64 v[0:1], 12, v[0:1]
	v_lshl_add_u64 v[0:1], s[24:25], 0, v[0:1]
	v_lshl_add_u64 v[0:1], v[0:1], 0, s[96:97]
	v_lshl_add_u64 v[0:1], v[92:93], 1, v[0:1]
	global_load_dwordx4 v[68:71], v[0:1], off
	s_mov_b32 s11, 0
	v_mov_b32_e32 v73, v72
	s_waitcnt vmcnt(0)
	v_mov_b64_e32 v[64:65], v[68:69]
	v_mov_b64_e32 v[66:67], v[70:71]

.LBB0_953:
	v_mfma_f32_32x32x16_bf16 v[0:15], v[68:71], v[48:51], 0
	v_mfma_f32_32x32x16_bf16 v[32:47], v[68:71], v[56:59], 0
	v_mfma_f32_32x32x16_bf16 v[16:31], v[68:71], v[52:55], 0
	v_mfma_f32_32x32x16_bf16 v[144:159], v[68:71], v[60:63], 0
	s_nop 9
	v_permlane32_swap_b32_e32 v0, v32
	v_permlane32_swap_b32_e32 v1, v33
	v_permlane32_swap_b32_e32 v2, v34
	v_permlane32_swap_b32_e32 v3, v35
	v_permlane32_swap_b32_e32 v4, v36
	v_permlane32_swap_b32_e32 v5, v37
	v_permlane32_swap_b32_e32 v6, v38
	v_permlane32_swap_b32_e32 v7, v39
	v_permlane32_swap_b32_e32 v8, v40
	v_permlane32_swap_b32_e32 v9, v41
	v_permlane32_swap_b32_e32 v10, v42
	v_permlane32_swap_b32_e32 v11, v43
	v_permlane32_swap_b32_e32 v12, v44
	v_permlane32_swap_b32_e32 v13, v45
	v_permlane32_swap_b32_e32 v14, v46
	v_permlane32_swap_b32_e32 v15, v47
	v_permlane32_swap_b32_e32 v16, v144
	v_permlane32_swap_b32_e32 v17, v145
	v_permlane32_swap_b32_e32 v18, v146
	v_permlane32_swap_b32_e32 v19, v147
	v_permlane32_swap_b32_e32 v20, v148
	v_permlane32_swap_b32_e32 v21, v149
	v_permlane32_swap_b32_e32 v22, v150
	v_permlane32_swap_b32_e32 v23, v151
	v_permlane32_swap_b32_e32 v24, v152
	v_permlane32_swap_b32_e32 v25, v153
	v_permlane32_swap_b32_e32 v26, v154
	v_permlane32_swap_b32_e32 v27, v155
	v_permlane32_swap_b32_e32 v28, v156
	v_permlane32_swap_b32_e32 v29, v157
	v_permlane32_swap_b32_e32 v30, v158
	v_permlane32_swap_b32_e32 v31, v159
	v_fmac_f32_e32 v0, v106, v73
	v_fmac_f32_e32 v16, v107, v72
	v_fmac_f32_e32 v0, v108, v72
	v_fmac_f32_e32 v16, v109, v73
	v_fmac_f32_e32 v1, v106, v16
	v_fmac_f32_e32 v17, v107, v0
	v_fmac_f32_e32 v1, v108, v0
	v_fmac_f32_e32 v17, v109, v16
	v_fmac_f32_e32 v2, v106, v17
	v_fmac_f32_e32 v18, v107, v1
	v_fmac_f32_e32 v2, v108, v1
	v_fmac_f32_e32 v18, v109, v17
	v_fmac_f32_e32 v3, v106, v18
	v_fmac_f32_e32 v19, v107, v2
	v_fmac_f32_e32 v3, v108, v2
	v_fmac_f32_e32 v19, v109, v18
	v_fmac_f32_e32 v32, v106, v19
	v_fmac_f32_e32 v144, v107, v3
	v_fmac_f32_e32 v32, v108, v3
	v_fmac_f32_e32 v144, v109, v19
	v_fmac_f32_e32 v33, v106, v144
	v_fmac_f32_e32 v145, v107, v32
	v_fmac_f32_e32 v33, v108, v32
	v_fmac_f32_e32 v145, v109, v144
	v_fmac_f32_e32 v34, v106, v145
	v_fmac_f32_e32 v146, v107, v33
	v_fmac_f32_e32 v34, v108, v33
	v_fmac_f32_e32 v146, v109, v145
	v_fmac_f32_e32 v35, v106, v146
	v_fmac_f32_e32 v147, v107, v34
	v_fmac_f32_e32 v35, v108, v34
	v_fmac_f32_e32 v147, v109, v146
	v_fmac_f32_e32 v4, v106, v147
	v_fmac_f32_e32 v20, v107, v35
	v_fmac_f32_e32 v4, v108, v35
	v_fmac_f32_e32 v20, v109, v147
	v_fmac_f32_e32 v5, v106, v20
	v_fmac_f32_e32 v21, v107, v4
	v_fmac_f32_e32 v5, v108, v4
	v_fmac_f32_e32 v21, v109, v20
	v_fmac_f32_e32 v6, v106, v21
	v_fmac_f32_e32 v22, v107, v5
	v_fmac_f32_e32 v6, v108, v5
	v_fmac_f32_e32 v22, v109, v21
	v_fmac_f32_e32 v7, v106, v22
	v_fmac_f32_e32 v23, v107, v6
	v_fmac_f32_e32 v7, v108, v6
	v_fmac_f32_e32 v23, v109, v22
	v_fmac_f32_e32 v36, v106, v23
	v_fmac_f32_e32 v148, v107, v7
	v_fmac_f32_e32 v36, v108, v7
	v_fmac_f32_e32 v148, v109, v23
	v_fmac_f32_e32 v37, v106, v148
	v_fmac_f32_e32 v149, v107, v36
	v_fmac_f32_e32 v37, v108, v36
	v_fmac_f32_e32 v149, v109, v148
	v_fmac_f32_e32 v38, v106, v149
	v_fmac_f32_e32 v150, v107, v37
	v_fmac_f32_e32 v38, v108, v37
	v_fmac_f32_e32 v150, v109, v149
	v_fmac_f32_e32 v39, v106, v150
	v_fmac_f32_e32 v151, v107, v38
	v_fmac_f32_e32 v39, v108, v38
	v_fmac_f32_e32 v151, v109, v150
	v_fmac_f32_e32 v8, v106, v151
	v_fmac_f32_e32 v24, v107, v39
	v_fmac_f32_e32 v8, v108, v39
	v_fmac_f32_e32 v24, v109, v151
	v_fmac_f32_e32 v9, v106, v24
	v_fmac_f32_e32 v25, v107, v8
	v_fmac_f32_e32 v9, v108, v8
	v_fmac_f32_e32 v25, v109, v24
	v_fmac_f32_e32 v10, v106, v25
	v_fmac_f32_e32 v26, v107, v9
	v_fmac_f32_e32 v10, v108, v9
	v_fmac_f32_e32 v26, v109, v25
	v_fmac_f32_e32 v11, v106, v26
	v_fmac_f32_e32 v27, v107, v10
	v_fmac_f32_e32 v11, v108, v10
	v_fmac_f32_e32 v27, v109, v26
	v_fmac_f32_e32 v40, v106, v27
	v_fmac_f32_e32 v152, v107, v11
	v_fmac_f32_e32 v40, v108, v11
	v_fmac_f32_e32 v152, v109, v27
	v_fmac_f32_e32 v41, v106, v152
	v_fmac_f32_e32 v153, v107, v40
	v_fmac_f32_e32 v41, v108, v40
	v_fmac_f32_e32 v153, v109, v152
	v_fmac_f32_e32 v42, v106, v153
	v_fmac_f32_e32 v154, v107, v41
	v_fmac_f32_e32 v42, v108, v41
	v_fmac_f32_e32 v154, v109, v153
	v_fmac_f32_e32 v43, v106, v154
	v_fmac_f32_e32 v155, v107, v42
	v_fmac_f32_e32 v43, v108, v42
	v_fmac_f32_e32 v155, v109, v154
	v_fmac_f32_e32 v12, v106, v155
	v_fmac_f32_e32 v28, v107, v43
	v_fmac_f32_e32 v12, v108, v43
	v_fmac_f32_e32 v28, v109, v155
	v_fmac_f32_e32 v13, v106, v28
	v_fmac_f32_e32 v29, v107, v12
	v_fmac_f32_e32 v13, v108, v12
	v_fmac_f32_e32 v29, v109, v28
	v_fmac_f32_e32 v14, v106, v29
	v_fmac_f32_e32 v30, v107, v13
	v_fmac_f32_e32 v14, v108, v13
	v_fmac_f32_e32 v30, v109, v29
	v_fmac_f32_e32 v15, v106, v30
	v_fmac_f32_e32 v31, v107, v14
	v_fmac_f32_e32 v15, v108, v14
	v_fmac_f32_e32 v31, v109, v30
	v_fmac_f32_e32 v44, v106, v31
	v_fmac_f32_e32 v156, v107, v15
	v_fmac_f32_e32 v44, v108, v15
	v_fmac_f32_e32 v156, v109, v31
	v_fmac_f32_e32 v45, v106, v156
	v_fmac_f32_e32 v157, v107, v44
	v_fmac_f32_e32 v45, v108, v44
	v_fmac_f32_e32 v157, v109, v156
	v_fmac_f32_e32 v46, v106, v157
	v_fmac_f32_e32 v158, v107, v45
	v_fmac_f32_e32 v46, v108, v45
	v_fmac_f32_e32 v158, v109, v157
	v_fmac_f32_e32 v47, v106, v158
	v_fmac_f32_e32 v159, v107, v46
	v_fmac_f32_e32 v47, v108, v46
	v_fmac_f32_e32 v159, v109, v158
	v_mov_b32_e32 v72, v47
	v_mov_b32_e32 v73, v159
	s_add_i32 s11, s11, 1
	s_waitcnt vmcnt(0)
	v_mov_b64_e32 v[70:71], v[66:67]
	s_cmp_lg_u32 s11, 8
	v_mov_b64_e32 v[68:69], v[64:65]
	s_cbranch_scc1 .LBB0_951
	s_lshl_b64 s[10:11], s[12:13], 6
	s_lshl_b32 s12, s37, 1
	s_or_b32 s10, s10, s12
	s_or_b64 s[10:11], s[10:11], s[22:23]
	s_lshl_b64 s[10:11], s[10:11], 9
	v_lshl_add_u64 v[0:1], v[104:105], 0, s[10:11]
	global_store_dwordx2 v[0:1], v[72:73], off

.LBB0_1057:
	v_mfma_f32_32x32x16_bf16 v[0:15], v[84:87], v[72:75], 0
	v_mfma_f32_32x32x16_bf16 v[32:47], v[84:87], v[48:51], 0
	v_mfma_f32_32x32x16_bf16 v[16:31], v[84:87], v[76:79], 0
	v_mfma_f32_32x32x16_bf16 v[144:159], v[84:87], v[52:55], 0
	s_nop 9
	v_permlane32_swap_b32_e32 v0, v32
	v_permlane32_swap_b32_e32 v1, v33
	v_permlane32_swap_b32_e32 v2, v34
	v_permlane32_swap_b32_e32 v3, v35
	v_permlane32_swap_b32_e32 v4, v36
	v_permlane32_swap_b32_e32 v5, v37
	v_permlane32_swap_b32_e32 v6, v38
	v_permlane32_swap_b32_e32 v7, v39
	v_permlane32_swap_b32_e32 v8, v40
	v_permlane32_swap_b32_e32 v9, v41
	v_permlane32_swap_b32_e32 v10, v42
	v_permlane32_swap_b32_e32 v11, v43
	v_permlane32_swap_b32_e32 v12, v44
	v_permlane32_swap_b32_e32 v13, v45
	v_permlane32_swap_b32_e32 v14, v46
	v_permlane32_swap_b32_e32 v15, v47
	v_permlane32_swap_b32_e32 v16, v144
	v_permlane32_swap_b32_e32 v17, v145
	v_permlane32_swap_b32_e32 v18, v146
	v_permlane32_swap_b32_e32 v19, v147
	v_permlane32_swap_b32_e32 v20, v148
	v_permlane32_swap_b32_e32 v21, v149
	v_permlane32_swap_b32_e32 v22, v150
	v_permlane32_swap_b32_e32 v23, v151
	v_permlane32_swap_b32_e32 v24, v152
	v_permlane32_swap_b32_e32 v25, v153
	v_permlane32_swap_b32_e32 v26, v154
	v_permlane32_swap_b32_e32 v27, v155
	v_permlane32_swap_b32_e32 v28, v156
	v_permlane32_swap_b32_e32 v29, v157
	v_permlane32_swap_b32_e32 v30, v158
	v_permlane32_swap_b32_e32 v31, v159
	v_fmac_f32_e32 v0, v108, v107
	v_fmac_f32_e32 v16, v109, v106
	v_fmac_f32_e32 v0, v114, v106
	v_fmac_f32_e32 v16, v115, v107
	v_cvt_pk_bf16_f32 v160, v0, v16
	ds_write_b32 v101, v160
	v_fmac_f32_e32 v1, v108, v16
	v_fmac_f32_e32 v17, v109, v0
	v_fmac_f32_e32 v1, v114, v0
	v_fmac_f32_e32 v17, v115, v16
	v_cvt_pk_bf16_f32 v161, v1, v17
	ds_write_b32 v101, v161 offset:528
	v_fmac_f32_e32 v2, v108, v17
	v_fmac_f32_e32 v18, v109, v1
	v_fmac_f32_e32 v2, v114, v1
	v_fmac_f32_e32 v18, v115, v17
	v_cvt_pk_bf16_f32 v162, v2, v18
	ds_write_b32 v101, v162 offset:1056
	v_fmac_f32_e32 v3, v108, v18
	v_fmac_f32_e32 v19, v109, v2
	v_fmac_f32_e32 v3, v114, v2
	v_fmac_f32_e32 v19, v115, v18
	v_cvt_pk_bf16_f32 v163, v3, v19
	ds_write_b32 v101, v163 offset:1584
	v_fmac_f32_e32 v32, v108, v19
	v_fmac_f32_e32 v144, v109, v3
	v_fmac_f32_e32 v32, v114, v3
	v_fmac_f32_e32 v144, v115, v19
	v_cvt_pk_bf16_f32 v160, v32, v144
	ds_write_b32 v101, v160 offset:2112
	v_fmac_f32_e32 v33, v108, v144
	v_fmac_f32_e32 v145, v109, v32
	v_fmac_f32_e32 v33, v114, v32
	v_fmac_f32_e32 v145, v115, v144
	v_cvt_pk_bf16_f32 v161, v33, v145
	ds_write_b32 v101, v161 offset:2640
	v_fmac_f32_e32 v34, v108, v145
	v_fmac_f32_e32 v146, v109, v33
	v_fmac_f32_e32 v34, v114, v33
	v_fmac_f32_e32 v146, v115, v145
	v_cvt_pk_bf16_f32 v162, v34, v146
	ds_write_b32 v101, v162 offset:3168
	v_fmac_f32_e32 v35, v108, v146
	v_fmac_f32_e32 v147, v109, v34
	v_fmac_f32_e32 v35, v114, v34
	v_fmac_f32_e32 v147, v115, v146
	v_cvt_pk_bf16_f32 v163, v35, v147
	ds_write_b32 v101, v163 offset:3696
	v_fmac_f32_e32 v4, v108, v147
	v_fmac_f32_e32 v20, v109, v35
	v_fmac_f32_e32 v4, v114, v35
	v_fmac_f32_e32 v20, v115, v147
	v_cvt_pk_bf16_f32 v160, v4, v20
	ds_write_b32 v101, v160 offset:4224
	v_fmac_f32_e32 v5, v108, v20
	v_fmac_f32_e32 v21, v109, v4
	v_fmac_f32_e32 v5, v114, v4
	v_fmac_f32_e32 v21, v115, v20
	v_cvt_pk_bf16_f32 v161, v5, v21
	ds_write_b32 v101, v161 offset:4752
	v_fmac_f32_e32 v6, v108, v21
	v_fmac_f32_e32 v22, v109, v5
	v_fmac_f32_e32 v6, v114, v5
	v_fmac_f32_e32 v22, v115, v21
	v_cvt_pk_bf16_f32 v162, v6, v22
	ds_write_b32 v101, v162 offset:5280
	v_fmac_f32_e32 v7, v108, v22
	v_fmac_f32_e32 v23, v109, v6
	v_fmac_f32_e32 v7, v114, v6
	v_fmac_f32_e32 v23, v115, v22
	v_cvt_pk_bf16_f32 v163, v7, v23
	ds_write_b32 v101, v163 offset:5808
	v_fmac_f32_e32 v36, v108, v23
	v_fmac_f32_e32 v148, v109, v7
	v_fmac_f32_e32 v36, v114, v7
	v_fmac_f32_e32 v148, v115, v23
	v_cvt_pk_bf16_f32 v160, v36, v148
	ds_write_b32 v101, v160 offset:6336
	v_fmac_f32_e32 v37, v108, v148
	v_fmac_f32_e32 v149, v109, v36
	v_fmac_f32_e32 v37, v114, v36
	v_fmac_f32_e32 v149, v115, v148
	v_cvt_pk_bf16_f32 v161, v37, v149
	ds_write_b32 v101, v161 offset:6864
	v_fmac_f32_e32 v38, v108, v149
	v_fmac_f32_e32 v150, v109, v37
	v_fmac_f32_e32 v38, v114, v37
	v_fmac_f32_e32 v150, v115, v149
	v_cvt_pk_bf16_f32 v162, v38, v150
	ds_write_b32 v101, v162 offset:7392
	v_fmac_f32_e32 v39, v108, v150
	v_fmac_f32_e32 v151, v109, v38
	v_fmac_f32_e32 v39, v114, v38
	v_fmac_f32_e32 v151, v115, v150
	v_cvt_pk_bf16_f32 v163, v39, v151
	ds_write_b32 v101, v163 offset:7920
	v_fmac_f32_e32 v8, v108, v151
	v_fmac_f32_e32 v24, v109, v39
	v_fmac_f32_e32 v8, v114, v39
	v_fmac_f32_e32 v24, v115, v151
	v_cvt_pk_bf16_f32 v160, v8, v24
	ds_write_b32 v101, v160 offset:8448
	v_fmac_f32_e32 v9, v108, v24
	v_fmac_f32_e32 v25, v109, v8
	v_fmac_f32_e32 v9, v114, v8
	v_fmac_f32_e32 v25, v115, v24
	v_cvt_pk_bf16_f32 v161, v9, v25
	ds_write_b32 v101, v161 offset:8976
	v_fmac_f32_e32 v10, v108, v25
	v_fmac_f32_e32 v26, v109, v9
	v_fmac_f32_e32 v10, v114, v9
	v_fmac_f32_e32 v26, v115, v25
	v_cvt_pk_bf16_f32 v162, v10, v26
	ds_write_b32 v101, v162 offset:9504
	v_fmac_f32_e32 v11, v108, v26
	v_fmac_f32_e32 v27, v109, v10
	v_fmac_f32_e32 v11, v114, v10
	v_fmac_f32_e32 v27, v115, v26
	v_cvt_pk_bf16_f32 v163, v11, v27
	ds_write_b32 v101, v163 offset:10032
	v_fmac_f32_e32 v40, v108, v27
	v_fmac_f32_e32 v152, v109, v11
	v_fmac_f32_e32 v40, v114, v11
	v_fmac_f32_e32 v152, v115, v27
	v_cvt_pk_bf16_f32 v160, v40, v152
	ds_write_b32 v101, v160 offset:10560
	v_fmac_f32_e32 v41, v108, v152
	v_fmac_f32_e32 v153, v109, v40
	v_fmac_f32_e32 v41, v114, v40
	v_fmac_f32_e32 v153, v115, v152
	v_cvt_pk_bf16_f32 v161, v41, v153
	ds_write_b32 v101, v161 offset:11088
	v_fmac_f32_e32 v42, v108, v153
	v_fmac_f32_e32 v154, v109, v41
	v_fmac_f32_e32 v42, v114, v41
	v_fmac_f32_e32 v154, v115, v153
	v_cvt_pk_bf16_f32 v162, v42, v154
	ds_write_b32 v101, v162 offset:11616
	v_fmac_f32_e32 v43, v108, v154
	v_fmac_f32_e32 v155, v109, v42
	v_fmac_f32_e32 v43, v114, v42
	v_fmac_f32_e32 v155, v115, v154
	v_cvt_pk_bf16_f32 v163, v43, v155
	ds_write_b32 v101, v163 offset:12144
	v_fmac_f32_e32 v12, v108, v155
	v_fmac_f32_e32 v28, v109, v43
	v_fmac_f32_e32 v12, v114, v43
	v_fmac_f32_e32 v28, v115, v155
	v_cvt_pk_bf16_f32 v160, v12, v28
	ds_write_b32 v101, v160 offset:12672
	v_fmac_f32_e32 v13, v108, v28
	v_fmac_f32_e32 v29, v109, v12
	v_fmac_f32_e32 v13, v114, v12
	v_fmac_f32_e32 v29, v115, v28
	v_cvt_pk_bf16_f32 v161, v13, v29
	ds_write_b32 v101, v161 offset:13200
	v_fmac_f32_e32 v14, v108, v29
	v_fmac_f32_e32 v30, v109, v13
	v_fmac_f32_e32 v14, v114, v13
	v_fmac_f32_e32 v30, v115, v29
	v_cvt_pk_bf16_f32 v162, v14, v30
	ds_write_b32 v101, v162 offset:13728
	v_fmac_f32_e32 v15, v108, v30
	v_fmac_f32_e32 v31, v109, v14
	v_fmac_f32_e32 v15, v114, v14
	v_fmac_f32_e32 v31, v115, v30
	v_cvt_pk_bf16_f32 v163, v15, v31
	ds_write_b32 v101, v163 offset:14256
	v_fmac_f32_e32 v44, v108, v31
	v_fmac_f32_e32 v156, v109, v15
	v_fmac_f32_e32 v44, v114, v15
	v_fmac_f32_e32 v156, v115, v31
	v_cvt_pk_bf16_f32 v160, v44, v156
	ds_write_b32 v101, v160 offset:14784
	v_fmac_f32_e32 v45, v108, v156
	v_fmac_f32_e32 v157, v109, v44
	v_fmac_f32_e32 v45, v114, v44
	v_fmac_f32_e32 v157, v115, v156
	v_cvt_pk_bf16_f32 v161, v45, v157
	ds_write_b32 v101, v161 offset:15312
	v_fmac_f32_e32 v46, v108, v157
	v_fmac_f32_e32 v158, v109, v45
	v_fmac_f32_e32 v46, v114, v45
	v_fmac_f32_e32 v158, v115, v157
	v_cvt_pk_bf16_f32 v162, v46, v158
	ds_write_b32 v101, v162 offset:15840
	v_fmac_f32_e32 v47, v108, v158
	v_fmac_f32_e32 v159, v109, v46
	v_fmac_f32_e32 v47, v114, v46
	v_fmac_f32_e32 v159, v115, v158
	v_cvt_pk_bf16_f32 v163, v47, v159
	ds_write_b32 v101, v163 offset:16368
	v_mov_b32_e32 v106, v47
	v_mov_b32_e32 v107, v159
	s_waitcnt lgkmcnt(0)
	ds_read_b128 v[0:3], v124
	ds_read_b128 v[4:7], v124 offset:64
	v_lshl_add_u32 v8, s14, 5, v98
	s_add_i32 s14, s14, 1
	s_waitcnt vmcnt(0)
	v_mov_b64_e32 v[86:87], v[82:83]
	s_cmp_lg_u32 s14, 8
	v_mov_b64_e32 v[84:85], v[80:81]
	s_waitcnt lgkmcnt(1)
	v_mfma_f32_16x16x32_bf16 v[0:3], v[0:3], v[56:59], 0
	s_waitcnt lgkmcnt(0)
	v_mfma_f32_16x16x32_bf16 v[0:3], v[4:7], v[60:63], v[0:3]
	ds_read_b128 v[4:7], v124 offset:128
	s_waitcnt lgkmcnt(0)
	v_mfma_f32_16x16x32_bf16 v[0:3], v[4:7], v[64:67], v[0:3]
	ds_read_b128 v[4:7], v124 offset:192
	s_waitcnt lgkmcnt(0)
	v_mfma_f32_16x16x32_bf16 v[0:3], v[4:7], v[68:71], v[0:3]
	v_sub_u32_e32 v4, 0xff, v8
	v_cndmask_b32_e64 v4, v4, v8, s[8:9]
	v_add_u32_e32 v4, s13, v4
	v_ashrrev_i32_e32 v5, 31, v4
	v_lshlrev_b64 v[4:5], 11, v[4:5]
	v_lshl_add_u64 v[4:5], v[112:113], 0, v[4:5]
	s_nop 1
	global_store_dword v[4:5], v0, off
	v_or_b32_e32 v0, 1, v8
	v_sub_u32_e32 v4, 0xff, v0
	v_cndmask_b32_e64 v0, v4, v0, s[8:9]
	v_add_u32_e32 v4, s13, v0
	v_ashrrev_i32_e32 v5, 31, v4
	v_lshlrev_b64 v[4:5], 11, v[4:5]
	v_lshl_add_u64 v[4:5], v[112:113], 0, v[4:5]
	v_or_b32_e32 v0, 2, v8
	global_store_dword v[4:5], v1, off
	v_sub_u32_e32 v1, 0xff, v0
	v_cndmask_b32_e64 v0, v1, v0, s[8:9]
	v_add_u32_e32 v0, s13, v0
	v_ashrrev_i32_e32 v1, 31, v0
	v_lshlrev_b64 v[0:1], 11, v[0:1]
	v_lshl_add_u64 v[0:1], v[112:113], 0, v[0:1]
	global_store_dword v[0:1], v2, off
	v_or_b32_e32 v0, 3, v8
	v_sub_u32_e32 v1, 0xff, v0
	v_cndmask_b32_e64 v0, v1, v0, s[8:9]
	v_add_u32_e32 v0, s13, v0
	v_ashrrev_i32_e32 v1, 31, v0
	v_lshlrev_b64 v[0:1], 11, v[0:1]
	v_lshl_add_u64 v[0:1], v[112:113], 0, v[0:1]
	global_store_dword v[0:1], v3, off
	ds_read_b128 v[0:3], v124 offset:8448
	ds_read_b128 v[4:7], v124 offset:8512
	s_waitcnt lgkmcnt(1)
	v_mfma_f32_16x16x32_bf16 v[0:3], v[0:3], v[56:59], 0
	s_waitcnt lgkmcnt(0)
	v_mfma_f32_16x16x32_bf16 v[0:3], v[4:7], v[60:63], v[0:3]
	ds_read_b128 v[4:7], v124 offset:8576
	s_waitcnt lgkmcnt(0)
	v_mfma_f32_16x16x32_bf16 v[0:3], v[4:7], v[64:67], v[0:3]
	ds_read_b128 v[4:7], v124 offset:8640
	s_waitcnt lgkmcnt(0)
	v_mfma_f32_16x16x32_bf16 v[0:3], v[4:7], v[68:71], v[0:3]
	v_add_u32_e32 v4, 16, v8
	v_sub_u32_e32 v5, 0xef, v8
	v_cndmask_b32_e64 v4, v5, v4, s[8:9]
	v_add_u32_e32 v4, s13, v4
	v_ashrrev_i32_e32 v5, 31, v4
	v_lshlrev_b64 v[4:5], 11, v[4:5]
	v_lshl_add_u64 v[4:5], v[112:113], 0, v[4:5]
	s_nop 0
	global_store_dword v[4:5], v0, off
	v_add_u32_e32 v0, 17, v8
	v_sub_u32_e32 v4, 0xee, v8
	v_cndmask_b32_e64 v0, v4, v0, s[8:9]
	v_add_u32_e32 v4, s13, v0
	v_ashrrev_i32_e32 v5, 31, v4
	v_lshlrev_b64 v[4:5], 11, v[4:5]
	v_lshl_add_u64 v[4:5], v[112:113], 0, v[4:5]
	global_store_dword v[4:5], v1, off
	v_add_u32_e32 v0, 18, v8
	v_sub_u32_e32 v1, 0xed, v8
	v_cndmask_b32_e64 v0, v1, v0, s[8:9]
	v_add_u32_e32 v0, s13, v0
	v_ashrrev_i32_e32 v1, 31, v0
	v_lshlrev_b64 v[0:1], 11, v[0:1]
	v_lshl_add_u64 v[0:1], v[112:113], 0, v[0:1]
	global_store_dword v[0:1], v2, off
	v_add_u32_e32 v0, 19, v8
	v_sub_u32_e32 v1, 0xec, v8
	v_cndmask_b32_e64 v0, v1, v0, s[8:9]
	v_add_u32_e32 v0, s13, v0
	v_ashrrev_i32_e32 v1, 31, v0
	v_lshlrev_b64 v[0:1], 11, v[0:1]
	v_lshl_add_u64 v[0:1], v[112:113], 0, v[0:1]
	global_store_dword v[0:1], v3, off
	s_waitcnt lgkmcnt(0)
	s_cbranch_scc1 .LBB0_1055
	s_and_b64 vcc, exec, s[10:11]
	s_cbranch_vccnz .LBB0_1062
	s_ashr_i32 s13, s12, 31
	s_lshl_b64 s[10:11], s[12:13], 13
	s_or_b64 s[10:11], s[10:11], s[80:81]
	s_add_u32 s10, s10, s96
	s_addc_u32 s11, s11, 0
	v_lshl_add_u64 v[0:1], s[10:11], 0, v[88:89]
	v_lshlrev_b64 v[0:1], 2, v[0:1]
	s_load_dwordx2 s[10:11], s[4:5], 0x100
	s_waitcnt lgkmcnt(0)
	s_nop 0
	v_lshl_add_u64 v[2:3], s[10:11], 0, v[0:1]
	v_add_co_u32_e32 v2, vcc, 0x4000000, v2
	s_nop 1
	v_addc_co_u32_e32 v3, vcc, 0, v3, vcc
	global_store_dword v[2:3], v106, off
	s_load_dwordx2 s[10:11], s[4:5], 0x100
	s_waitcnt lgkmcnt(0)
	s_nop 0
	v_lshl_add_u64 v[0:1], s[10:11], 0, v[0:1]
	v_add_co_u32_e32 v0, vcc, 0x4100000, v0
	s_nop 1
	v_addc_co_u32_e32 v1, vcc, 0, v1, vcc
	global_store_dword v[0:1], v107, off
